# speedup vs baseline: 1.0087x; 1.0022x over previous
;     __device__ __forceinline__ bf16_t* Ksf() const { return (bf16_t*)(ws + OFF_Ksf); }
; DEV void st_bf4(bf16_t* p, float a, float b, float c, float d) { uint2 w; w.x = pk_bf16(a, b); w.y = pk_bf16(c, d); *(uint2*)p = w; }
; DEV void cache_convert(const Params& p, int l, int vb, int vnb, float* sm) {
;     ...
;     for (int i = gt; i < 8 * PAST * 96; i += gn) {
;         const int b = i / (PAST * 96), rem = i % (PAST * 96);
;         const float4 v = *(const float4*)(p.cache_fox_k + ((size_t)(l * 8 + b) * PAST * 384) + (size_t)rem * 4);
;         st_bf4(p.Ksf() + (size_t)b * KSP * 384 + (size_t)rem * 4, v.x, v.y, v.z, v.w);
;     }
.LBB0_2711:
	s_mov_b32 s10, 0x17ffff
	v_add_u32_e32 v121, s8, v1
	v_add_u32_e32 v133, s8, v121
	v_add_u32_e32 v145, s8, v133
	v_min_i32_e32 v121, s10, v121
	v_min_i32_e32 v133, s10, v133
	v_min_i32_e32 v145, s10, v145
	v_mul_hi_i32 v100, v1, s13
	v_lshrrev_b32_e32 v101, 31, v100
	v_ashrrev_i32_e32 v100, 15, v100
	v_add_u32_e32 v108, v100, v101
	v_mul_i32_i24_e32 v100, 0x30000, v108
	v_add_u32_e32 v102, s9, v108
	v_sub_u32_e32 v104, v1, v100
	v_mul_hi_i32_i24_e32 v101, 0x300000, v102
	v_mul_i32_i24_e32 v100, 0x300000, v102
	v_lshl_add_u64 v[100:101], s[70:71], 0, v[100:101]
	v_ashrrev_i32_e32 v105, 31, v104
	v_lshl_add_u64 v[100:101], v[104:105], 4, v[100:101]
	v_mul_hi_i32 v112, v121, s13
	v_lshrrev_b32_e32 v113, 31, v112
	v_ashrrev_i32_e32 v112, 15, v112
	v_add_u32_e32 v120, v112, v113
	v_mul_i32_i24_e32 v112, 0x30000, v120
	v_add_u32_e32 v114, s9, v120
	v_sub_u32_e32 v116, v121, v112
	v_mul_hi_i32_i24_e32 v113, 0x300000, v114
	v_mul_i32_i24_e32 v112, 0x300000, v114
	v_lshl_add_u64 v[112:113], s[70:71], 0, v[112:113]
	v_ashrrev_i32_e32 v117, 31, v116
	v_lshl_add_u64 v[112:113], v[116:117], 4, v[112:113]
	v_mul_hi_i32 v124, v133, s13
	v_lshrrev_b32_e32 v125, 31, v124
	v_ashrrev_i32_e32 v124, 15, v124
	v_add_u32_e32 v132, v124, v125
	v_mul_i32_i24_e32 v124, 0x30000, v132
	v_add_u32_e32 v126, s9, v132
	v_sub_u32_e32 v128, v133, v124
	v_mul_hi_i32_i24_e32 v125, 0x300000, v126
	v_mul_i32_i24_e32 v124, 0x300000, v126
	v_lshl_add_u64 v[124:125], s[70:71], 0, v[124:125]
	v_ashrrev_i32_e32 v129, 31, v128
	v_lshl_add_u64 v[124:125], v[128:129], 4, v[124:125]
	v_mul_hi_i32 v136, v145, s13
	v_lshrrev_b32_e32 v137, 31, v136
	v_ashrrev_i32_e32 v136, 15, v136
	v_add_u32_e32 v144, v136, v137
	v_mul_i32_i24_e32 v136, 0x30000, v144
	v_add_u32_e32 v138, s9, v144
	v_sub_u32_e32 v140, v145, v136
	v_mul_hi_i32_i24_e32 v137, 0x300000, v138
	v_mul_i32_i24_e32 v136, 0x300000, v138
	v_lshl_add_u64 v[136:137], s[70:71], 0, v[136:137]
	v_ashrrev_i32_e32 v141, 31, v140
	v_lshl_add_u64 v[136:137], v[140:141], 4, v[136:137]
	flat_load_dwordx4 v[100:103], v[100:101]
	flat_load_dwordx4 v[112:115], v[112:113]
	flat_load_dwordx4 v[124:127], v[124:125]
	flat_load_dwordx4 v[136:139], v[136:137]
	v_mov_b64_e32 v[106:107], s[2:3]
	v_mul_i32_i24_e32 v108, 0x840, v108
	v_mad_i64_i32 v[106:107], s[10:11], v108, s12, v[106:107]
	v_lshl_add_u64 v[104:105], v[104:105], 3, v[106:107]
	v_mov_b64_e32 v[118:119], s[2:3]
	v_mul_i32_i24_e32 v120, 0x840, v120
	v_mad_i64_i32 v[118:119], s[10:11], v120, s12, v[118:119]
	v_lshl_add_u64 v[116:117], v[116:117], 3, v[118:119]
	v_mov_b64_e32 v[130:131], s[2:3]
	v_mul_i32_i24_e32 v132, 0x840, v132
	v_mad_i64_i32 v[130:131], s[10:11], v132, s12, v[130:131]
	v_lshl_add_u64 v[128:129], v[128:129], 3, v[130:131]
	v_mov_b64_e32 v[142:143], s[2:3]
	v_mul_i32_i24_e32 v144, 0x840, v144
	v_mad_i64_i32 v[142:143], s[10:11], v144, s12, v[142:143]
	v_lshl_add_u64 v[140:141], v[140:141], 3, v[142:143]
	v_lshl_add_u32 v1, s8, 2, v1
	s_mov_b32 s10, 0x17ffff
	v_cmp_lt_i32_e32 vcc, s10, v1
	s_or_b64 s[4:5], vcc, s[4:5]
	s_waitcnt vmcnt(0) lgkmcnt(0)
	v_cvt_pk_bf16_f32 v100, v100, v101
	v_cvt_pk_bf16_f32 v101, v102, v103
	flat_store_dwordx2 v[104:105], v[100:101]
	v_cvt_pk_bf16_f32 v112, v112, v113
	v_cvt_pk_bf16_f32 v113, v114, v115
	flat_store_dwordx2 v[116:117], v[112:113]
	v_cvt_pk_bf16_f32 v124, v124, v125
	v_cvt_pk_bf16_f32 v125, v126, v127
	flat_store_dwordx2 v[128:129], v[124:125]
	v_cvt_pk_bf16_f32 v136, v136, v137
	v_cvt_pk_bf16_f32 v137, v138, v139
	flat_store_dwordx2 v[140:141], v[136:137]
	s_andn2_b64 exec, exec, s[4:5]
	s_cbranch_execnz .LBB0_2711

;     __device__ __forceinline__ bf16_t* Ksb() const { return (bf16_t*)(ws + OFF_Ksb); }
; DEV void st_bf4(bf16_t* p, float a, float b, float c, float d) { uint2 w; w.x = pk_bf16(a, b); w.y = pk_bf16(c, d); *(uint2*)p = w; }
; DEV void cache_convert(const Params& p, int l, int vb, int vnb, float* sm) {
;     ...
;     for (int i = gt; i < 8 * PAST * 64; i += gn) {
;         const int b = i / (PAST * 64), rem = i % (PAST * 64);
;         const float4 v = *(const float4*)(p.cache_sb_k + ((size_t)(l * 8 + b) * PAST * 256) + (size_t)rem * 4);
;         st_bf4(p.Ksb() + (size_t)b * KSP * 256 + (size_t)rem * 4, v.x, v.y, v.z, v.w);
;     }
.LBB0_2714:
	s_mov_b32 s10, 0xfffff
	v_add_u32_e32 v121, s8, v1
	v_add_u32_e32 v133, s8, v121
	v_add_u32_e32 v145, s8, v133
	v_min_i32_e32 v121, s10, v121
	v_min_i32_e32 v133, s10, v133
	v_min_i32_e32 v145, s10, v145
	v_ashrrev_i32_e32 v100, 31, v1
	v_lshrrev_b32_e32 v100, 15, v100
	v_add_u32_e32 v100, v1, v100
	v_ashrrev_i32_e32 v108, 17, v100
	v_mul_i32_i24_e32 v101, 0x20000, v108
	v_add_u32_e32 v100, s9, v108
	v_sub_u32_e32 v104, v1, v101
	v_ashrrev_i32_e32 v101, 31, v100
	v_lshlrev_b64 v[100:101], 21, v[100:101]
	v_ashrrev_i32_e32 v105, 31, v104
	v_lshl_add_u64 v[100:101], s[96:97], 0, v[100:101]
	v_lshl_add_u64 v[100:101], v[104:105], 4, v[100:101]
	v_ashrrev_i32_e32 v112, 31, v121
	v_lshrrev_b32_e32 v112, 15, v112
	v_add_u32_e32 v112, v121, v112
	v_ashrrev_i32_e32 v120, 17, v112
	v_mul_i32_i24_e32 v113, 0x20000, v120
	v_add_u32_e32 v112, s9, v120
	v_sub_u32_e32 v116, v121, v113
	v_ashrrev_i32_e32 v113, 31, v112
	v_lshlrev_b64 v[112:113], 21, v[112:113]
	v_ashrrev_i32_e32 v117, 31, v116
	v_lshl_add_u64 v[112:113], s[96:97], 0, v[112:113]
	v_lshl_add_u64 v[112:113], v[116:117], 4, v[112:113]
	v_ashrrev_i32_e32 v124, 31, v133
	v_lshrrev_b32_e32 v124, 15, v124
	v_add_u32_e32 v124, v133, v124
	v_ashrrev_i32_e32 v132, 17, v124
	v_mul_i32_i24_e32 v125, 0x20000, v132
	v_add_u32_e32 v124, s9, v132
	v_sub_u32_e32 v128, v133, v125
	v_ashrrev_i32_e32 v125, 31, v124
	v_lshlrev_b64 v[124:125], 21, v[124:125]
	v_ashrrev_i32_e32 v129, 31, v128
	v_lshl_add_u64 v[124:125], s[96:97], 0, v[124:125]
	v_lshl_add_u64 v[124:125], v[128:129], 4, v[124:125]
	v_ashrrev_i32_e32 v136, 31, v145
	v_lshrrev_b32_e32 v136, 15, v136
	v_add_u32_e32 v136, v145, v136
	v_ashrrev_i32_e32 v144, 17, v136
	v_mul_i32_i24_e32 v137, 0x20000, v144
	v_add_u32_e32 v136, s9, v144
	v_sub_u32_e32 v140, v145, v137
	v_ashrrev_i32_e32 v137, 31, v136
	v_lshlrev_b64 v[136:137], 21, v[136:137]
	v_ashrrev_i32_e32 v141, 31, v140
	v_lshl_add_u64 v[136:137], s[96:97], 0, v[136:137]
	v_lshl_add_u64 v[136:137], v[140:141], 4, v[136:137]
	flat_load_dwordx4 v[100:103], v[100:101]
	flat_load_dwordx4 v[112:115], v[112:113]
	flat_load_dwordx4 v[124:127], v[124:125]
	flat_load_dwordx4 v[136:139], v[136:137]
	v_mul_i32_i24_e32 v108, 0x840, v108
	v_ashrrev_i32_e32 v107, 31, v108
	v_mov_b32_e32 v106, v108
	v_lshlrev_b64 v[106:107], 9, v[106:107]
	v_lshl_add_u64 v[106:107], s[2:3], 0, v[106:107]
	v_lshl_add_u64 v[104:105], v[104:105], 3, v[106:107]
	v_mul_i32_i24_e32 v120, 0x840, v120
	v_ashrrev_i32_e32 v119, 31, v120
	v_mov_b32_e32 v118, v120
	v_lshlrev_b64 v[118:119], 9, v[118:119]
	v_lshl_add_u64 v[118:119], s[2:3], 0, v[118:119]
	v_lshl_add_u64 v[116:117], v[116:117], 3, v[118:119]
	v_mul_i32_i24_e32 v132, 0x840, v132
	v_ashrrev_i32_e32 v131, 31, v132
	v_mov_b32_e32 v130, v132
	v_lshlrev_b64 v[130:131], 9, v[130:131]
	v_lshl_add_u64 v[130:131], s[2:3], 0, v[130:131]
	v_lshl_add_u64 v[128:129], v[128:129], 3, v[130:131]
	v_mul_i32_i24_e32 v144, 0x840, v144
	v_ashrrev_i32_e32 v143, 31, v144
	v_mov_b32_e32 v142, v144
	v_lshlrev_b64 v[142:143], 9, v[142:143]
	v_lshl_add_u64 v[142:143], s[2:3], 0, v[142:143]
	v_lshl_add_u64 v[140:141], v[140:141], 3, v[142:143]
	v_lshl_add_u32 v1, s8, 2, v1
	s_mov_b32 s10, 0xfffff
	v_cmp_lt_i32_e32 vcc, s10, v1
	s_or_b64 s[4:5], vcc, s[4:5]
	s_waitcnt vmcnt(0) lgkmcnt(0)
	v_cvt_pk_bf16_f32 v100, v100, v101
	v_cvt_pk_bf16_f32 v101, v102, v103
	flat_store_dwordx2 v[104:105], v[100:101]
	v_cvt_pk_bf16_f32 v112, v112, v113
	v_cvt_pk_bf16_f32 v113, v114, v115
	flat_store_dwordx2 v[116:117], v[112:113]
	v_cvt_pk_bf16_f32 v124, v124, v125
	v_cvt_pk_bf16_f32 v125, v126, v127
	flat_store_dwordx2 v[128:129], v[124:125]
	v_cvt_pk_bf16_f32 v136, v136, v137
	v_cvt_pk_bf16_f32 v137, v138, v139
	flat_store_dwordx2 v[140:141], v[136:137]
	s_andn2_b64 exec, exec, s[4:5]
	s_cbranch_execnz .LBB0_2714
